# hand-written indexer score loop: scalar loop control, K-fragment copy+prefetch in the MFMA shadow, relu+weighted head sum in 32 VALU, half-wave sums via one permlane swap per query pair
# speedup vs baseline: 1.1290x; 1.0354x over previous
; DI void lds_barrier() { asm volatile("s_waitcnt lgkmcnt(0)" ::: "memory"); __builtin_amdgcn_s_barrier(); asm volatile("" ::: "memory"); }
; DI void selectA_item(const Params& p, int item, int next_item, char* lds, bf16x8 (&qf)[4], float (&wq)[16]) {
;     ...
;   const f32x4 pcv = ((const f32x4*)p.in[I_P])[(size_t)item * 512 + tid];
;   if (tid < 4) { mm[tid * 2] = 0xFFFFFFFFu; mm[tid * 2 + 1] = 0u; }
;   lds_barrier();
;   const bf16* Kt = (const bf16*)(p.ws + WS_IKS) + (size_t)b * 256 * 2048 + lane * 8;
;   {
;     bf16x8 kf[4], kn[4];
; #pragma unroll
;     for (int t = 0; t < 4; ++t) { kf[t] = (bf16x8){0, 0, 0, 0, 0, 0, 0, 0}; kn[t] = kf[t]; }
;     if (wid < ntile) {
; #pragma unroll
;       for (int t = 0; t < 4; ++t) kf[t] = *(const bf16x8*)(Kt + (size_t)wid * 2048 + t * 512);
;     }
;     float lo0 = INFINITY, hi0 = -INFINITY, lo1 = INFINITY, hi1 = -INFINITY;
;     for (int kt = wid; kt < ntile; kt += 8) {
;       if (kt + 8 < ntile) {
; #pragma unroll
;         for (int t = 0; t < 4; ++t) kn[t] = *(const bf16x8*)(Kt + (size_t)(kt + 8) * 2048 + t * 512);
;       }
.LBB0_405:
	s_andn2_b64 vcc, exec, s[4:5]
	s_cbranch_vccnz .LBB0_402
	v_readlane_b32 s4, v254, 3
	v_mov_b32_e32 v72, v182
	v_readlane_b32 s5, v254, 4
	s_load_dwordx2 s[4:5], s[4:5], 0x8
	s_ashr_i32 s3, s2, 31
	s_lshl_b64 s[6:7], s[2:3], 9
	v_ashrrev_i32_e32 v73, 31, v72
	v_lshl_add_u64 v[76:77], s[6:7], 0, v[72:73]
	s_waitcnt lgkmcnt(0)
	v_lshl_add_u64 v[0:1], v[76:77], 4, s[4:5]
	global_load_dwordx4 v[16:19], v[0:1], off
	v_cmp_gt_i32_e32 vcc, 4, v72
	s_and_saveexec_b64 s[4:5], vcc
	v_lshl_add_u32 v0, v72, 3, 0
	v_add_u32_e32 v0, 0x24060, v0
	ds_write_b64 v0, v[114:115]
	s_or_b64 exec, exec, s[4:5]
	s_ashr_i32 s52, s2, 11
	s_lshl_b32 s2, s2, 2
	s_and_b32 s2, s2, 0x1ffc
	v_writelane_b32 v254, s2, 58
	s_add_i32 s2, s2, 35
	s_waitcnt lgkmcnt(0)
	s_barrier
	v_ashrrev_i32_e32 v68, 6, v72
	s_lshr_b32 s8, s2, 5
	v_and_b32_e32 v67, 63, v72
	v_bfe_u32 v71, v72, 5, 1
	s_ashr_i32 s53, s52, 31
	v_cmp_gt_i32_e32 vcc, s8, v68
	s_and_saveexec_b64 s[2:3], vcc
	s_cbranch_execz .LBB0_415
	s_lshl_b64 s[4:5], s[52:53], 20
	v_readlane_b32 s6, v254, 24
	s_add_u32 s6, s6, s4
	v_readlane_b32 s7, v254, 25
	s_addc_u32 s7, s7, s5
	v_lshlrev_b32_e32 v48, 4, v67
	v_ashrrev_i32_e32 v69, 31, v68
	v_lshl_add_u64 v[0:1], s[6:7], 0, v[48:49]
	v_lshlrev_b64 v[4:5], 12, v[68:69]
	v_lshl_add_u64 v[6:7], v[0:1], 0, v[4:5]
	global_load_dwordx4 v[116:119], v[6:7], off
	global_load_dwordx4 v[62:65], v[6:7], off offset:1024
	global_load_dwordx4 v[58:61], v[6:7], off offset:2048
	global_load_dwordx4 v[54:57], v[6:7], off offset:3072
	v_lshlrev_b32_e32 v6, 7, v68
	v_mov_b32_e32 v48, v49
	v_and_b32_e32 v69, 31, v72
	v_lshl_add_u32 v6, v71, 16, v6
	v_lshl_add_u64 v[4:5], s[4:5], 0, v[4:5]
	v_readlane_b32 s4, v254, 47
	v_mov_b32_e32 v50, v49
	v_mov_b32_e32 v51, v49
	v_mov_b64_e32 v[20:21], v[48:49]
	v_mov_b64_e32 v[24:25], v[48:49]
	v_mov_b64_e32 v[28:29], v[48:49]
	v_lshl_or_b32 v6, v69, 2, v6
	v_lshl_or_b32 v4, v67, 4, v4
	v_readlane_b32 s5, v254, 48
	v_mov_b64_e32 v[22:23], v[50:51]
	v_mov_b64_e32 v[26:27], v[50:51]
	v_mov_b64_e32 v[30:31], v[50:51]
	v_mov_b64_e32 v[52:53], v[50:51]
	v_cmp_gt_u32_e32 vcc, 32, v67
	v_add_u32_e32 v79, 0, v6
	v_lshl_add_u64 v[80:81], s[4:5], 0, v[4:5]
	v_mov_b32_e32 v73, 0xff800000
	v_mov_b32_e32 v83, 0x7f800000
	s_mov_b64 s[4:5], 0
	v_mov_b64_e32 v[50:51], v[48:49]
	v_mov_b32_e32 v75, 0x7f800000
	v_mov_b32_e32 v48, 0xff800000
	v_mov_b32_e32 v84, v68
	v_readfirstlane_b32 s9, v68
	s_add_i32 s10, s9, 8
	s_cmp_lt_i32 s10, s8
	s_cbranch_scc0 .Lsc_nopre
	global_load_dwordx4 v[20:23], v[80:81], off offset:-2048
	global_load_dwordx4 v[24:27], v[80:81], off offset:-1024
	global_load_dwordx4 v[28:31], v[80:81], off
	global_load_dwordx4 v[50:53], v[80:81], off offset:1024
	s_mov_b64 s[6:7], 0x8000
	v_lshl_add_u64 v[80:81], v[80:81], 0, s[6:7]
	s_waitcnt vmcnt(4)
	s_branch .Lsc_loop

; DI f32x16 mfma32(bf16x8 a, bf16x8 b, f32x16 c) { return __builtin_amdgcn_mfma_f32_32x32x16_bf16(a, b, c, 0, 0, 0); }
; DI float half_sum(float v) { auto rr = __builtin_amdgcn_permlane32_swap(__float_as_uint(v), __float_as_uint(v), false, false); return __uint_as_float(rr[0]) + __uint_as_float(rr[1]); }
; DI void selectA_item(const Params& p, int item, int next_item, char* lds, bf16x8 (&qf)[4], float (&wq)[16]) {
;     ...
;     for (int kt = wid; kt < ntile; kt += 8) {
;       if (kt + 8 < ntile) {
; #pragma unroll
;         for (int t = 0; t < 4; ++t) kn[t] = *(const bf16x8*)(Kt + (size_t)(kt + 8) * 2048 + t * 512);
;       }
;       f32x16 s;
; #pragma unroll
;       for (int i = 0; i < 16; ++i) s[i] = 0.f;
; #pragma unroll
;       for (int t = 0; t < 4; ++t) s = mfma32(qf[t], kf[t], s);
;       float v[4];
; #pragma unroll
;       for (int q = 0; q < 4; ++q) {
;         float a = wq[4 * q] * fmaxf(s[4 * q], 0.f);
; #pragma unroll
;         for (int jj = 1; jj < 4; ++jj) a += wq[4 * q + jj] * fmaxf(s[4 * q + jj], 0.f);
;         v[q] = half_sum(a) + 0.f;
;       }
;       const float va = h ? v[2] : v[0], vb = h ? v[3] : v[1];
;       const int key = kt * 32 + r32;
;       sc[(2 * h) * 8192 + key] = va; sc[(2 * h + 1) * 8192 + key] = vb;
;       lo0 = fminf(lo0, va); hi0 = fmaxf(hi0, va); lo1 = fminf(lo1, vb); hi1 = fmaxf(hi1, vb);
; #pragma unroll
;       for (int t = 0; t < 4; ++t) kf[t] = kn[t];
;     }
.Lsc_loop:
	v_mfma_f32_32x32x16_bf16 v[0:15], v[32:35], v[116:119], 0
	v_mfma_f32_32x32x16_bf16 v[0:15], v[36:39], v[62:65], v[0:15]
	v_mfma_f32_32x32x16_bf16 v[0:15], v[40:43], v[58:61], v[0:15]
	v_mfma_f32_32x32x16_bf16 v[0:15], v[44:47], v[54:57], v[0:15]
	s_add_i32 s9, s9, 8
	s_cmp_lt_i32 s9, s8
	s_cbranch_scc0 .Lsc_last
	s_waitcnt vmcnt(0)
	v_mov_b64_e32 v[116:117], v[20:21]
	v_mov_b64_e32 v[118:119], v[22:23]
	v_mov_b64_e32 v[62:63], v[24:25]
	v_mov_b64_e32 v[64:65], v[26:27]
	v_mov_b64_e32 v[58:59], v[28:29]
	v_mov_b64_e32 v[60:61], v[30:31]
	v_mov_b64_e32 v[54:55], v[50:51]
	v_mov_b64_e32 v[56:57], v[52:53]
	s_add_i32 s10, s9, 8
	s_cmp_lt_i32 s10, s8
	s_cbranch_scc0 .Lsc_noload
	global_load_dwordx4 v[20:23], v[80:81], off offset:-2048
	global_load_dwordx4 v[24:27], v[80:81], off offset:-1024
	global_load_dwordx4 v[28:31], v[80:81], off
	global_load_dwordx4 v[50:53], v[80:81], off offset:1024
	s_mov_b64 s[6:7], 0x8000
	v_lshl_add_u64 v[80:81], v[80:81], 0, s[6:7]
.Lsc_noload:
	v_max_f32_e32 v0, 0, v0
	v_max_f32_e32 v1, 0, v1
	v_max_f32_e32 v2, 0, v2
	v_max_f32_e32 v3, 0, v3
	v_max_f32_e32 v4, 0, v4
	v_max_f32_e32 v5, 0, v5
	v_max_f32_e32 v6, 0, v6
	v_max_f32_e32 v7, 0, v7
	v_max_f32_e32 v8, 0, v8
	v_max_f32_e32 v9, 0, v9
	v_max_f32_e32 v10, 0, v10
	v_max_f32_e32 v11, 0, v11
	v_max_f32_e32 v12, 0, v12
	v_max_f32_e32 v13, 0, v13
	v_max_f32_e32 v14, 0, v14
	v_max_f32_e32 v15, 0, v15
	v_mul_f32_e32 v0, v106, v0
	v_mul_f32_e32 v4, v108, v4
	v_mul_f32_e32 v8, v110, v8
	v_mul_f32_e32 v12, v112, v12
	v_fmac_f32_e32 v0, v107, v1
	v_fmac_f32_e32 v4, v109, v5
	v_fmac_f32_e32 v8, v111, v9
	v_fmac_f32_e32 v12, v113, v13
	v_fmac_f32_e32 v0, v104, v2
	v_fmac_f32_e32 v4, v102, v6
	v_fmac_f32_e32 v8, v100, v10
	v_fmac_f32_e32 v12, v98, v14
	v_fmac_f32_e32 v0, v105, v3
	v_fmac_f32_e32 v4, v103, v7
	v_fmac_f32_e32 v8, v101, v11
	v_fmac_f32_e32 v12, v99, v15
	s_nop 1
	v_permlane32_swap_b32_e32 v0, v8
	v_permlane32_swap_b32_e32 v4, v12
	v_add_f32_e32 v0, v0, v8
	v_add_f32_e32 v4, v4, v12
	ds_write2st64_b32 v79, v0, v4 offset1:128
	v_min_f32_e32 v83, v83, v0
	v_max_f32_e32 v73, v73, v0
	v_min_f32_e32 v75, v75, v4
	v_max_f32_e32 v48, v48, v4
	v_add_u32_e32 v79, 0x400, v79
	s_branch .Lsc_loop
.Lsc_last:
	s_nop 8
	v_max_f32_e32 v0, 0, v0
	v_max_f32_e32 v1, 0, v1
	v_max_f32_e32 v2, 0, v2
	v_max_f32_e32 v3, 0, v3
	v_max_f32_e32 v4, 0, v4
	v_max_f32_e32 v5, 0, v5
	v_max_f32_e32 v6, 0, v6
	v_max_f32_e32 v7, 0, v7
	v_max_f32_e32 v8, 0, v8
	v_max_f32_e32 v9, 0, v9
	v_max_f32_e32 v10, 0, v10
	v_max_f32_e32 v11, 0, v11
	v_max_f32_e32 v12, 0, v12
	v_max_f32_e32 v13, 0, v13
	v_max_f32_e32 v14, 0, v14
	v_max_f32_e32 v15, 0, v15
	v_mul_f32_e32 v0, v106, v0
	v_mul_f32_e32 v4, v108, v4
	v_mul_f32_e32 v8, v110, v8
	v_mul_f32_e32 v12, v112, v12
	v_fmac_f32_e32 v0, v107, v1
	v_fmac_f32_e32 v4, v109, v5
	v_fmac_f32_e32 v8, v111, v9
	v_fmac_f32_e32 v12, v113, v13
	v_fmac_f32_e32 v0, v104, v2
	v_fmac_f32_e32 v4, v102, v6
	v_fmac_f32_e32 v8, v100, v10
	v_fmac_f32_e32 v12, v98, v14
	v_fmac_f32_e32 v0, v105, v3
	v_fmac_f32_e32 v4, v103, v7
	v_fmac_f32_e32 v8, v101, v11
	v_fmac_f32_e32 v12, v99, v15
	s_nop 1
	v_permlane32_swap_b32_e32 v0, v8
	v_permlane32_swap_b32_e32 v4, v12
	v_add_f32_e32 v0, v0, v8
	v_add_f32_e32 v4, v4, v12
	ds_write2st64_b32 v79, v0, v4 offset1:128
	v_min_f32_e32 v83, v83, v0
	v_max_f32_e32 v73, v73, v0
	v_min_f32_e32 v75, v75, v4
	v_max_f32_e32 v48, v48, v4
	v_add_u32_e32 v79, 0x400, v79
; DI unsigned f2ord(float f) { f += 0.f; const unsigned u = __float_as_uint(f); return (u & 0x80000000u) ? ~u : (u | 0x80000000u); }
; DI void selectA_item(const Params& p, int item, int next_item, char* lds, bf16x8 (&qf)[4], float (&wq)[16]) {
;     ...
;     if (wid < ntile) {
; #pragma unroll
;       for (int o = 1; o < 32; o <<= 1) { lo0 = fminf(lo0, __shfl_xor(lo0, o)); hi0 = fmaxf(hi0, __shfl_xor(hi0, o)); lo1 = fminf(lo1, __shfl_xor(lo1, o)); hi1 = fmaxf(hi1, __shfl_xor(hi1, o)); }
;       if (r32 == 0) { atomicMin(&mm[(2 * h) * 2], f2ord(lo0)); atomicMax(&mm[(2 * h) * 2 + 1], f2ord(hi0)); atomicMin(&mm[(2 * h + 1) * 2], f2ord(lo1)); atomicMax(&mm[(2 * h + 1) * 2 + 1], f2ord(hi1)); }
;     }
.Lsc_exit:
	v_and_b32_e32 v0, 64, v183
	v_add_u32_e32 v3, 64, v0
	v_xor_b32_e32 v0, 1, v183
	v_cmp_lt_i32_e32 vcc, v0, v3
	v_max_f32_e32 v4, v83, v83
	v_max_f32_e32 v5, v73, v73
	v_cndmask_b32_e32 v0, v183, v0, vcc
	v_lshlrev_b32_e32 v0, 2, v0
	ds_bpermute_b32 v1, v0, v83
	ds_bpermute_b32 v2, v0, v73
	v_max_f32_e32 v7, v48, v48
	s_waitcnt lgkmcnt(1)
	v_max_f32_e32 v1, v1, v1
	v_min_f32_e32 v1, v4, v1
	ds_bpermute_b32 v4, v0, v75
	s_waitcnt lgkmcnt(1)
	v_max_f32_e32 v2, v2, v2
	v_max_f32_e32 v2, v5, v2
	v_max_f32_e32 v5, v75, v75
	ds_bpermute_b32 v0, v0, v48
	s_waitcnt lgkmcnt(1)
	v_max_f32_e32 v4, v4, v4
	v_min_f32_e32 v4, v5, v4
	v_xor_b32_e32 v5, 2, v183
	v_cmp_lt_i32_e32 vcc, v5, v3
	s_waitcnt lgkmcnt(0)
	v_max_f32_e32 v0, v0, v0
	v_max_f32_e32 v0, v7, v0
	v_cndmask_b32_e32 v5, v183, v5, vcc
	v_lshlrev_b32_e32 v5, 2, v5
	ds_bpermute_b32 v6, v5, v1
	ds_bpermute_b32 v8, v5, v2
	ds_bpermute_b32 v7, v5, v4
	ds_bpermute_b32 v5, v5, v0
	s_waitcnt lgkmcnt(3)
	v_max_f32_e32 v6, v6, v6
	v_min_f32_e32 v1, v1, v6
	s_waitcnt lgkmcnt(2)
	v_max_f32_e32 v6, v8, v8
	v_max_f32_e32 v2, v2, v6
	s_waitcnt lgkmcnt(1)
	v_max_f32_e32 v6, v7, v7
	v_min_f32_e32 v4, v4, v6
	v_xor_b32_e32 v6, 4, v183
	v_cmp_lt_i32_e32 vcc, v6, v3
	s_waitcnt lgkmcnt(0)
	v_max_f32_e32 v5, v5, v5
	v_max_f32_e32 v0, v0, v5
	v_cndmask_b32_e32 v6, v183, v6, vcc
	v_lshlrev_b32_e32 v6, 2, v6
	ds_bpermute_b32 v7, v6, v1
	ds_bpermute_b32 v8, v6, v2
	ds_bpermute_b32 v5, v6, v4
	ds_bpermute_b32 v6, v6, v0
	s_waitcnt lgkmcnt(3)
	v_max_f32_e32 v7, v7, v7
	v_min_f32_e32 v1, v1, v7
	s_waitcnt lgkmcnt(2)
	v_max_f32_e32 v7, v8, v8
	v_max_f32_e32 v2, v2, v7
	v_xor_b32_e32 v7, 8, v183
	v_cmp_lt_i32_e32 vcc, v7, v3
	s_waitcnt lgkmcnt(1)
	v_max_f32_e32 v5, v5, v5
	v_min_f32_e32 v4, v4, v5
	v_cndmask_b32_e32 v7, v183, v7, vcc
	v_lshlrev_b32_e32 v7, 2, v7
	ds_bpermute_b32 v8, v7, v1
	s_waitcnt lgkmcnt(1)
	v_max_f32_e32 v5, v6, v6
	ds_bpermute_b32 v6, v7, v2
	v_max_f32_e32 v5, v0, v5
	s_waitcnt lgkmcnt(1)
	v_max_f32_e32 v0, v8, v8
	ds_bpermute_b32 v8, v7, v4
	ds_bpermute_b32 v7, v7, v5
	v_min_f32_e32 v0, v1, v0
	s_waitcnt lgkmcnt(2)
	v_max_f32_e32 v1, v6, v6
	v_max_f32_e32 v1, v2, v1
	s_waitcnt lgkmcnt(1)
	v_max_f32_e32 v2, v8, v8
	v_min_f32_e32 v2, v4, v2
	s_waitcnt lgkmcnt(0)
	v_max_f32_e32 v4, v7, v7
	v_max_f32_e32 v4, v5, v4
	v_xor_b32_e32 v5, 16, v183
	v_cmp_lt_i32_e32 vcc, v5, v3
	s_nop 1
	v_cndmask_b32_e32 v3, v183, v5, vcc
	v_lshlrev_b32_e32 v7, 2, v3
	ds_bpermute_b32 v3, v7, v0
	ds_bpermute_b32 v5, v7, v1
	ds_bpermute_b32 v6, v7, v2
	ds_bpermute_b32 v7, v7, v4
	v_cmp_eq_u32_e32 vcc, 0, v69
	s_and_b64 exec, exec, vcc
	s_cbranch_execz .LBB0_415
	s_waitcnt lgkmcnt(0)
	v_max_f32_e32 v7, v7, v7
	v_max_f32_e32 v4, v4, v4
	v_max_f32_e32 v8, v4, v7
	v_max_f32_e32 v4, v6, v6
	v_max_f32_e32 v2, v2, v2
	v_min_f32_e32 v9, v2, v4
	v_max_f32_e32 v2, v5, v5
	v_max_f32_e32 v1, v1, v1
	v_max_f32_e32 v2, v1, v2
	v_max_f32_e32 v1, v3, v3
	v_max_f32_e32 v0, v0, v0
	v_min_f32_e32 v3, v0, v1
	v_lshl_add_u32 v0, v71, 4, 0
	v_add_u32_e32 v4, 0x24060, v0
	v_pk_add_f32 v[0:1], v[2:3], 0 op_sel_hi:[1,0]
	s_nop 0
	v_not_b32_e32 v2, v1
	v_or_b32_e32 v3, 0x80000000, v1
	v_cmp_gt_i32_e32 vcc, 0, v1
	s_nop 1
	v_cndmask_b32_e32 v1, v3, v2, vcc
	ds_min_u32 v4, v1
	v_not_b32_e32 v1, v0
	v_or_b32_e32 v2, 0x80000000, v0
	v_cmp_gt_i32_e32 vcc, 0, v0
	s_nop 1
	v_cndmask_b32_e32 v0, v2, v1, vcc
	ds_max_u32 v4, v0 offset:4
	v_pk_add_f32 v[0:1], v[8:9], 0 op_sel_hi:[1,0]
	s_nop 0
	v_not_b32_e32 v2, v1
	v_or_b32_e32 v3, 0x80000000, v1
	v_cmp_gt_i32_e32 vcc, 0, v1
	s_nop 1
	v_cndmask_b32_e32 v1, v3, v2, vcc
	ds_min_u32 v4, v1 offset:8
	v_not_b32_e32 v1, v0
	v_or_b32_e32 v2, 0x80000000, v0
	v_cmp_gt_i32_e32 vcc, 0, v0
	s_nop 1
	v_cndmask_b32_e32 v0, v2, v1, vcc
	ds_max_u32 v4, v0 offset:12
